# plus: no cache invalidate in the row-statistics exchanges (slots are read with sc1 loads); sample-row producers store write-through (sc1) so flag publication needs no L2 writeback
# speedup vs baseline: 1.0705x; 1.0351x over previous
.LBB0_651:
	s_ashr_i32 s45, s75, 2
	s_and_b32 s22, s45, -4
	s_or_b32 s16, s22, s28
	s_ashr_i32 s17, s16, 31
	s_lshl_b64 s[12:13], s[16:17], 11
	s_add_u32 s12, s14, s12
	s_addc_u32 s13, s15, s13
	s_lshl_b32 s20, s76, 9
	s_add_u32 s52, s12, s20
	s_addc_u32 s53, s13, 0
	s_ashr_i32 s23, s22, 31
	v_lshl_add_u64 v[20:21], v[6:7], 0, s[20:21]
	s_lshl_b64 s[12:13], s[22:23], 11
	v_lshl_add_u64 v[14:15], v[20:21], 0, s[12:13]
	global_load_dword v22, v0, s[52:53]
	global_load_dword v24, v[14:15], off
	s_or_b32 s17, s22, s76
	s_or_b32 s44, s22, 1
	s_or_b32 s48, s22, 2
	s_or_b32 s50, s45, 3
	s_lshl_b32 s54, s17, 3
	s_ashr_i32 s45, s44, 31
	s_ashr_i32 s49, s48, 31
	s_ashr_i32 s51, s50, 31
	s_ashr_i32 s55, s54, 31
	s_lshl_b64 s[22:23], s[44:45], 11
	s_lshl_b64 s[44:45], s[48:49], 11
	s_lshl_b64 s[48:49], s[50:51], 11
	s_lshl_b64 s[50:51], s[54:55], 3
	v_lshl_add_u64 v[12:13], v[10:11], 0, s[20:21]
	s_or_b32 s20, s50, s28
	s_mul_i32 s17, s51, 0x210
	s_mul_hi_u32 s51, s20, 0x210
	s_mulk_i32 s20, 0x210
	s_add_i32 s51, s51, s17
	s_add_u32 s68, s24, s20
	s_addc_u32 s69, s25, s51
	s_or_b32 s56, s54, 1
	s_ashr_i32 s57, s56, 31
	s_lshl_b64 s[66:67], s[56:57], 3
	s_or_b32 s20, s66, s28
	s_mulk_i32 s67, 0x210
	s_mul_hi_u32 s51, s20, 0x210
	s_mulk_i32 s20, 0x210
	s_add_i32 s51, s51, s67
	s_add_u32 s70, s24, s20
	s_addc_u32 s71, s25, s51
	s_or_b32 s56, s54, 2
	s_ashr_i32 s57, s56, 31
	s_lshl_b64 s[56:57], s[56:57], 3
	v_lshl_add_u64 v[16:17], v[20:21], 0, s[22:23]
	s_or_b32 s51, s56, s28
	v_lshl_add_u64 v[18:19], v[20:21], 0, s[44:45]
	v_lshl_add_u64 v[20:21], v[20:21], 0, s[48:49]
	global_load_dword v25, v[16:17], off
	global_load_dword v26, v[18:19], off
	global_load_dword v27, v[20:21], off
	global_load_dword v62, v[20:21], off offset:256
	global_load_dword v63, v[18:19], off offset:256
	global_load_dword v64, v[16:17], off offset:256
	global_load_dword v65, v[14:15], off offset:256
	s_nop 0
	global_load_dwordx2 v[14:15], v1, s[68:69]
	global_load_dwordx2 v[16:17], v1, s[70:71]
	global_load_dword v66, v0, s[52:53] offset:256
	s_mul_i32 s20, s57, 0x210
	s_mul_hi_u32 s52, s51, 0x210
	s_mulk_i32 s51, 0x210
	s_add_i32 s53, s52, s20
	s_add_u32 s52, s24, s51
	s_addc_u32 s53, s25, s53
	s_or_b32 s58, s54, 3
	s_ashr_i32 s59, s58, 31
	s_lshl_b64 s[58:59], s[58:59], 3
	s_or_b32 s51, s58, s28
	s_mul_i32 s57, s59, 0x210
	s_mul_hi_u32 s55, s51, 0x210
	s_mulk_i32 s51, 0x210
	s_add_i32 s55, s55, s57
	s_add_u32 s80, s24, s51
	s_addc_u32 s81, s25, s55
	s_or_b32 s60, s54, 4
	s_ashr_i32 s61, s60, 31
	s_lshl_b64 s[60:61], s[60:61], 3
	s_or_b32 s51, s60, s28
	s_mul_i32 s59, s61, 0x210
	s_mul_hi_u32 s55, s51, 0x210
	s_mulk_i32 s51, 0x210
	s_add_i32 s55, s55, s59
	s_add_u32 s82, s24, s51
	s_addc_u32 s83, s25, s55
	s_or_b32 s62, s54, 5
	s_ashr_i32 s63, s62, 31
	s_lshl_b64 s[62:63], s[62:63], 3
	s_or_b32 s51, s62, s28
	s_mul_hi_u32 s55, s51, 0x210
	s_mul_i32 s61, s63, 0x210
	s_add_i32 s55, s55, s61
	s_mulk_i32 s51, 0x210
	s_add_u32 s84, s24, s51
	s_addc_u32 s85, s25, s55
	s_or_b32 s64, s54, 6
	s_ashr_i32 s65, s64, 31
	s_lshl_b64 s[64:65], s[64:65], 3
	s_or_b32 s51, s64, s28
	s_mul_hi_u32 s55, s51, 0x210
	s_mul_i32 s63, s65, 0x210
	s_waitcnt vmcnt(10)
	v_mul_f32_e32 v18, v22, v24
	s_add_i32 s55, s55, s63
	s_mulk_i32 s51, 0x210
	v_mov_b32_dpp v18, v18 quad_perm:[1,0,3,2] row_mask:0xf bank_mask:0xf bound_ctrl:1
	s_add_u32 s86, s24, s51
	v_fmac_f32_e32 v18, v22, v24
	s_addc_u32 s87, s25, s55
	s_or_b32 s54, s54, 7
	v_add_f32_dpp v18, v18, v18 quad_perm:[2,3,0,1] row_mask:0xf bank_mask:0xf bound_ctrl:1
	s_ashr_i32 s55, s54, 31
	s_lshl_b64 s[54:55], s[54:55], 3
	v_add_f32_dpp v18, v18, v18 row_half_mirror row_mask:0xf bank_mask:0xf bound_ctrl:1
	s_or_b32 s51, s54, s28
	s_mul_hi_u32 s65, s51, 0x210
	v_add_f32_dpp v18, v18, v18 row_ror:8 row_mask:0xf bank_mask:0xf bound_ctrl:1
	v_mov_b32_e32 v19, v18
	s_mulk_i32 s55, 0x210
	s_nop 0
	v_permlane16_swap_b32_e32 v18, v19
	s_add_i32 s65, s65, s55
	s_mulk_i32 s51, 0x210
	v_add_f32_e32 v24, v18, v19
	global_load_dwordx2 v[18:19], v1, s[52:53]
	global_load_dwordx2 v[20:21], v1, s[80:81]
	global_load_dwordx2 v[38:39], v1, s[82:83]
	global_load_dwordx2 v[40:41], v1, s[84:85]
	s_add_u32 s88, s24, s51
	s_addc_u32 s89, s25, s65
	global_load_dwordx2 v[42:43], v1, s[86:87]
	global_load_dwordx2 v[44:45], v1, s[88:89]
	v_mov_b32_e32 v46, v24
	s_nop 1
	v_permlane32_swap_b32_e32 v24, v46
	v_add_f32_e32 v67, v24, v46
	global_load_dwordx2 v[46:47], v31, s[68:69] offset:16
	global_load_dwordx2 v[48:49], v31, s[70:71] offset:16
	global_load_dwordx2 v[50:51], v31, s[52:53] offset:16
	global_load_dwordx2 v[52:53], v31, s[80:81] offset:16
	global_load_dwordx2 v[54:55], v31, s[82:83] offset:16
	global_load_dwordx2 v[56:57], v31, s[84:85] offset:16
	global_load_dwordx2 v[58:59], v31, s[86:87] offset:16
	global_load_dwordx2 v[60:61], v31, s[88:89] offset:16
	s_waitcnt vmcnt(23)
	v_mul_f32_e32 v24, v22, v25
	v_fmac_f32_e32 v67, v37, v9
	s_or_b32 s50, s50, s29
	v_mov_b32_dpp v24, v24 quad_perm:[1,0,3,2] row_mask:0xf bank_mask:0xf bound_ctrl:1
	v_fmac_f32_e32 v24, v22, v25
	s_mul_hi_u32 s51, s50, 0x210
	s_add_i32 s51, s51, s17
	v_add_f32_dpp v24, v24, v24 quad_perm:[2,3,0,1] row_mask:0xf bank_mask:0xf bound_ctrl:1
	s_mulk_i32 s50, 0x210
	s_add_u32 s50, s24, s50
	v_add_f32_dpp v24, v24, v24 row_half_mirror row_mask:0xf bank_mask:0xf bound_ctrl:1
	s_addc_u32 s51, s25, s51
	s_or_b32 s17, s66, s29
	v_add_f32_dpp v24, v24, v24 row_ror:8 row_mask:0xf bank_mask:0xf bound_ctrl:1
	v_mov_b32_e32 v25, v24
	s_nop 1
	v_permlane16_swap_b32_e32 v24, v25
	v_add_f32_e32 v24, v24, v25
	v_mov_b32_e32 v25, v24
	s_nop 1
	v_permlane32_swap_b32_e32 v24, v25
	v_add_f32_e32 v24, v24, v25
	v_fmac_f32_e32 v24, v37, v23
	v_cndmask_b32_e64 v68, v24, v30, s[6:7]
	s_waitcnt vmcnt(22)
	v_mul_f32_e32 v24, v22, v26
	s_mul_hi_u32 s52, s17, 0x210
	s_add_i32 s53, s52, s67
	v_mov_b32_dpp v24, v24 quad_perm:[1,0,3,2] row_mask:0xf bank_mask:0xf bound_ctrl:1
	v_fmac_f32_e32 v24, v22, v26
	s_mulk_i32 s17, 0x210
	s_add_u32 s52, s24, s17
	v_add_f32_dpp v24, v24, v24 quad_perm:[2,3,0,1] row_mask:0xf bank_mask:0xf bound_ctrl:1
	s_addc_u32 s53, s25, s53
	s_nop 0
	v_add_f32_dpp v24, v24, v24 row_half_mirror row_mask:0xf bank_mask:0xf bound_ctrl:1
	s_nop 1
	v_add_f32_dpp v24, v24, v24 row_ror:8 row_mask:0xf bank_mask:0xf bound_ctrl:1
	v_mov_b32_e32 v25, v24
	s_nop 1
	v_permlane16_swap_b32_e32 v24, v25
	v_add_f32_e32 v24, v24, v25
	v_mov_b32_e32 v25, v24
	s_nop 1
	v_permlane32_swap_b32_e32 v24, v25
	v_add_f32_e32 v24, v24, v25
	v_fmac_f32_e32 v24, v37, v28
	v_cndmask_b32_e64 v69, v24, v30, s[8:9]
	s_waitcnt vmcnt(21)
	v_mul_f32_e32 v24, v22, v27
	s_nop 1
	v_mov_b32_dpp v24, v24 quad_perm:[1,0,3,2] row_mask:0xf bank_mask:0xf bound_ctrl:1
	v_fmac_f32_e32 v24, v22, v27
	s_nop 1
	v_add_f32_dpp v22, v24, v24 quad_perm:[2,3,0,1] row_mask:0xf bank_mask:0xf bound_ctrl:1
	s_nop 1
	v_add_f32_dpp v22, v22, v22 row_half_mirror row_mask:0xf bank_mask:0xf bound_ctrl:1
	s_nop 1
	v_add_f32_dpp v22, v22, v22 row_ror:8 row_mask:0xf bank_mask:0xf bound_ctrl:1
	v_mov_b32_e32 v24, v22
	s_nop 1
	v_permlane16_swap_b32_e32 v22, v24
	v_add_f32_e32 v22, v22, v24
	v_mov_b32_e32 v24, v22
	s_nop 1
	v_permlane32_swap_b32_e32 v22, v24
	v_add_f32_e32 v22, v22, v24
	v_fmac_f32_e32 v22, v37, v29
	v_cndmask_b32_e64 v70, v30, v22, s[10:11]
	v_max_f32_e32 v22, v67, v68
	v_max3_f32 v22, v22, v69, v70
	s_waitcnt vmcnt(15)
	v_max3_f32 v22, v22, v14, v16
	s_waitcnt vmcnt(12)
	v_max3_f32 v22, v22, v18, v20
	s_waitcnt vmcnt(10)
	v_max3_f32 v22, v22, v38, v40
	s_waitcnt vmcnt(8)
	v_max3_f32 v71, v22, v42, v44
	v_sub_f32_e32 v14, v14, v71
	v_exp_f32_e32 v14, v14
	v_sub_f32_e32 v16, v16, v71
	v_exp_f32_e32 v16, v16
	v_sub_f32_e32 v18, v18, v71
	v_exp_f32_e32 v18, v18
	v_sub_f32_e32 v20, v20, v71
	v_fma_f32 v72, v14, v15, 0
	v_sub_f32_e32 v15, v38, v71
	v_exp_f32_e32 v20, v20
	v_exp_f32_e32 v22, v15
	v_sub_f32_e32 v15, v40, v71
	v_exp_f32_e32 v38, v15
	v_sub_f32_e32 v15, v42, v71
	v_fmac_f32_e32 v72, v16, v17
	v_exp_f32_e32 v40, v15
	v_sub_f32_e32 v15, v44, v71
	v_fmac_f32_e32 v72, v18, v19
	v_exp_f32_e32 v42, v15
	s_waitcnt vmcnt(7)
	v_pk_fma_f32 v[14:15], v[14:15], v[46:47], 0 op_sel_hi:[0,1,0]
	v_fmac_f32_e32 v72, v20, v21
	s_waitcnt vmcnt(6)
	v_pk_fma_f32 v[14:15], v[16:17], v[48:49], v[14:15] op_sel_hi:[0,1,1]
	v_sub_f32_e32 v16, v67, v71
	v_fmac_f32_e32 v72, v22, v39
	v_exp_f32_e32 v16, v16
	v_sub_f32_e32 v17, v68, v71
	v_fmac_f32_e32 v72, v38, v41
	s_waitcnt vmcnt(5)
	v_pk_fma_f32 v[14:15], v[18:19], v[50:51], v[14:15] op_sel_hi:[0,1,1]
	v_exp_f32_e32 v18, v17
	v_sub_f32_e32 v17, v69, v71
	v_fmac_f32_e32 v72, v40, v43
	s_waitcnt vmcnt(4)
	v_pk_fma_f32 v[14:15], v[20:21], v[52:53], v[14:15] op_sel_hi:[0,1,1]
	v_exp_f32_e32 v20, v17
	v_sub_f32_e32 v17, v70, v71
	v_fmac_f32_e32 v72, v42, v45
	s_waitcnt vmcnt(3)
	v_pk_fma_f32 v[14:15], v[22:23], v[54:55], v[14:15] op_sel_hi:[0,1,1]
	v_exp_f32_e32 v22, v17
	v_add_f32_e32 v17, v16, v72
	v_add_f32_e32 v17, v18, v17
	v_add_f32_e32 v17, v20, v17
	v_add_f32_e32 v17, v22, v17
	s_waitcnt vmcnt(2)
	v_pk_fma_f32 v[14:15], v[38:39], v[56:57], v[14:15] op_sel_hi:[0,1,1]
	v_lshl_add_u64 v[38:39], v[12:13], 0, s[12:13]
	v_div_scale_f32 v19, s[12:13], v17, v17, 1.0
	s_or_b32 s12, s56, s29
	s_mul_hi_u32 s13, s12, 0x210
	s_add_i32 s13, s13, s20
	s_mulk_i32 s12, 0x210
	s_add_u32 s12, s24, s12
	s_addc_u32 s13, s25, s13
	s_or_b32 s17, s58, s29
	s_mul_hi_u32 s20, s17, 0x210
	s_add_i32 s20, s20, s57
	s_mulk_i32 s17, 0x210
	s_waitcnt vmcnt(1)
	v_pk_fma_f32 v[14:15], v[40:41], v[58:59], v[14:15] op_sel_hi:[0,1,1]
	v_lshl_add_u64 v[40:41], v[12:13], 0, s[22:23]
	s_add_u32 s22, s24, s17
	s_addc_u32 s23, s25, s20
	s_or_b32 s17, s60, s29
	s_mul_hi_u32 s20, s17, 0x210
	s_add_i32 s20, s20, s59
	s_mulk_i32 s17, 0x210
	s_waitcnt vmcnt(0)
	v_pk_fma_f32 v[14:15], v[42:43], v[60:61], v[14:15] op_sel_hi:[0,1,1]
	v_lshl_add_u64 v[42:43], v[12:13], 0, s[44:45]
	s_add_u32 s44, s24, s17
	s_addc_u32 s45, s25, s20
	s_or_b32 s17, s62, s29
	s_mul_hi_u32 s20, s17, 0x210
	v_rcp_f32_e32 v21, v19
	s_add_i32 s20, s20, s61
	s_mulk_i32 s17, 0x210
	v_lshl_add_u64 v[12:13], v[12:13], 0, s[48:49]
	s_add_u32 s48, s24, s17
	s_addc_u32 s49, s25, s20
	s_or_b32 s17, s64, s29
	s_mul_hi_u32 s20, s17, 0x210
	v_fma_f32 v44, -v19, v21, 1.0
	s_add_i32 s20, s20, s63
	s_mulk_i32 s17, 0x210
	v_fmac_f32_e32 v21, v44, v21
	v_div_scale_f32 v44, vcc, 1.0, v17, 1.0
	s_add_u32 s56, s24, s17
	v_mul_f32_e32 v73, v44, v21
	s_addc_u32 s57, s25, s20
	s_or_b32 s17, s54, s29
	global_load_dwordx2 v[24:25], v1, s[50:51]
	global_load_dwordx2 v[26:27], v1, s[52:53]
	v_fma_f32 v45, -v19, v73, v44
	v_mul_f32_e32 v56, v66, v65
	s_mul_hi_u32 s20, s17, 0x210
	v_fmac_f32_e32 v73, v45, v21
	s_add_i32 s20, s20, s55
	s_mulk_i32 s17, 0x210
	v_mov_b32_dpp v56, v56 quad_perm:[1,0,3,2] row_mask:0xf bank_mask:0xf bound_ctrl:1
	v_fma_f32 v19, -v19, v73, v44
	global_load_dwordx2 v[44:45], v1, s[12:13]
	global_load_dwordx2 v[46:47], v1, s[22:23]
	global_load_dwordx2 v[48:49], v1, s[44:45]
	global_load_dwordx2 v[50:51], v1, s[48:49]
	s_add_u32 s54, s24, s17
	v_fmac_f32_e32 v56, v66, v65
	s_addc_u32 s55, s25, s20
	global_load_dwordx2 v[52:53], v1, s[56:57]
	global_load_dwordx2 v[54:55], v1, s[54:55]
	v_add_f32_dpp v56, v56, v56 quad_perm:[2,3,0,1] row_mask:0xf bank_mask:0xf bound_ctrl:1
	v_div_fmas_f32 v19, v19, v21, v73
	v_div_fixup_f32 v80, v19, v17, 1.0
	v_add_f32_dpp v56, v56, v56 row_half_mirror row_mask:0xf bank_mask:0xf bound_ctrl:1
	s_nop 1
	v_add_f32_dpp v56, v56, v56 row_ror:8 row_mask:0xf bank_mask:0xf bound_ctrl:1
	v_mov_b32_e32 v57, v56
	s_nop 1
	v_permlane16_swap_b32_e32 v56, v57
	v_add_f32_e32 v56, v56, v57
	v_mov_b32_e32 v57, v56
	s_nop 1
	v_permlane32_swap_b32_e32 v56, v57
	v_add_f32_e32 v72, v56, v57
	v_mul_f32_e32 v56, v66, v64
	v_fmac_f32_e32 v72, v37, v9
	s_nop 0
	v_mov_b32_dpp v56, v56 quad_perm:[1,0,3,2] row_mask:0xf bank_mask:0xf bound_ctrl:1
	v_fmac_f32_e32 v56, v66, v64
	s_nop 1
	v_add_f32_dpp v56, v56, v56 quad_perm:[2,3,0,1] row_mask:0xf bank_mask:0xf bound_ctrl:1
	s_nop 1
	v_add_f32_dpp v56, v56, v56 row_half_mirror row_mask:0xf bank_mask:0xf bound_ctrl:1
	s_nop 1
	v_add_f32_dpp v56, v56, v56 row_ror:8 row_mask:0xf bank_mask:0xf bound_ctrl:1
	v_mov_b32_e32 v57, v56
	s_nop 1
	v_permlane16_swap_b32_e32 v56, v57
	v_add_f32_e32 v56, v56, v57
	v_mov_b32_e32 v57, v56
	s_nop 1
	v_permlane32_swap_b32_e32 v56, v57
	v_add_f32_e32 v56, v56, v57
	v_fmac_f32_e32 v56, v37, v23
	v_cndmask_b32_e64 v74, v56, v30, s[6:7]
	v_mul_f32_e32 v56, v66, v63
	s_nop 1
	v_mov_b32_dpp v56, v56 quad_perm:[1,0,3,2] row_mask:0xf bank_mask:0xf bound_ctrl:1
	v_fmac_f32_e32 v56, v66, v63
	s_nop 1
	v_add_f32_dpp v56, v56, v56 quad_perm:[2,3,0,1] row_mask:0xf bank_mask:0xf bound_ctrl:1
	s_nop 1
	v_add_f32_dpp v56, v56, v56 row_half_mirror row_mask:0xf bank_mask:0xf bound_ctrl:1
	s_nop 1
	v_add_f32_dpp v56, v56, v56 row_ror:8 row_mask:0xf bank_mask:0xf bound_ctrl:1
	v_mov_b32_e32 v57, v56
	s_nop 1
	v_permlane16_swap_b32_e32 v56, v57
	v_add_f32_e32 v56, v56, v57
	v_mov_b32_e32 v57, v56
	s_nop 1
	v_permlane32_swap_b32_e32 v56, v57
	v_add_f32_e32 v56, v56, v57
	v_fmac_f32_e32 v56, v37, v28
	v_cndmask_b32_e64 v75, v56, v30, s[8:9]
	v_mul_f32_e32 v56, v66, v62
	s_nop 1
	v_mov_b32_dpp v56, v56 quad_perm:[1,0,3,2] row_mask:0xf bank_mask:0xf bound_ctrl:1
	v_fmac_f32_e32 v56, v66, v62
	s_nop 1
	v_add_f32_dpp v56, v56, v56 quad_perm:[2,3,0,1] row_mask:0xf bank_mask:0xf bound_ctrl:1
	s_nop 1
	v_add_f32_dpp v56, v56, v56 row_half_mirror row_mask:0xf bank_mask:0xf bound_ctrl:1
	s_nop 1
	v_add_f32_dpp v76, v56, v56 row_ror:8 row_mask:0xf bank_mask:0xf bound_ctrl:1
	global_load_dwordx2 v[38:39], v[38:39], off
	s_nop 0
	global_load_dwordx2 v[40:41], v[40:41], off
	s_nop 0
	global_load_dwordx2 v[42:43], v[42:43], off
	s_nop 0
	global_load_dwordx2 v[12:13], v[12:13], off
	s_nop 0
	global_load_dwordx2 v[56:57], v31, s[50:51] offset:16
	global_load_dwordx2 v[58:59], v31, s[52:53] offset:16
	global_load_dwordx2 v[60:61], v31, s[12:13] offset:16
	global_load_dwordx2 v[62:63], v31, s[22:23] offset:16
	global_load_dwordx2 v[64:65], v31, s[44:45] offset:16
	global_load_dwordx2 v[66:67], v31, s[48:49] offset:16
	global_load_dwordx2 v[68:69], v31, s[56:57] offset:16
	global_load_dwordx2 v[70:71], v31, s[54:55] offset:16
	v_mov_b32_e32 v77, v76
	s_nop 1
	v_permlane16_swap_b32_e32 v76, v77
	v_add_f32_e32 v76, v76, v77
	v_mov_b32_e32 v77, v76
	s_nop 1
	v_permlane32_swap_b32_e32 v76, v77
	v_add_f32_e32 v76, v76, v77
	v_fmac_f32_e32 v76, v37, v29
	v_cndmask_b32_e64 v37, v30, v76, s[10:11]
	v_max_f32_e32 v76, v72, v74
	v_max3_f32 v76, v76, v75, v37
	s_waitcnt vmcnt(18)
	v_max3_f32 v76, v76, v24, v26
	s_waitcnt vmcnt(16)
	v_max3_f32 v76, v76, v44, v46
	s_waitcnt vmcnt(14)
	v_max3_f32 v76, v76, v48, v50
	s_waitcnt vmcnt(12)
	v_max3_f32 v77, v76, v52, v54
	v_sub_f32_e32 v24, v24, v77
	v_exp_f32_e32 v24, v24
	v_sub_f32_e32 v26, v26, v77
	v_exp_f32_e32 v26, v26
	v_sub_f32_e32 v44, v44, v77
	v_exp_f32_e32 v44, v44
	v_sub_f32_e32 v46, v46, v77
	v_fma_f32 v25, v24, v25, 0
	v_exp_f32_e32 v46, v46
	v_fmac_f32_e32 v25, v26, v27
	v_sub_f32_e32 v27, v48, v77
	v_exp_f32_e32 v48, v27
	v_sub_f32_e32 v27, v50, v77
	v_exp_f32_e32 v50, v27
	v_sub_f32_e32 v27, v52, v77
	v_fmac_f32_e32 v25, v44, v45
	v_exp_f32_e32 v52, v27
	v_sub_f32_e32 v27, v54, v77
	v_fmac_f32_e32 v25, v46, v47
	v_exp_f32_e32 v54, v27
	v_sub_f32_e32 v27, v72, v77
	v_fmac_f32_e32 v25, v48, v49
	v_exp_f32_e32 v72, v27
	v_sub_f32_e32 v27, v74, v77
	v_fmac_f32_e32 v25, v50, v51
	v_exp_f32_e32 v74, v27
	v_sub_f32_e32 v27, v75, v77
	v_fmac_f32_e32 v25, v52, v53
	v_exp_f32_e32 v76, v27
	v_sub_f32_e32 v27, v37, v77
	v_fmac_f32_e32 v25, v54, v55
	v_exp_f32_e32 v78, v27
	v_add_f32_e32 v25, v72, v25
	v_add_f32_e32 v25, v74, v25
	v_add_f32_e32 v25, v76, v25
	v_add_f32_e32 v25, v78, v25
	v_div_scale_f32 v27, s[12:13], v25, v25, 1.0
	v_rcp_f32_e32 v37, v27
	s_nop 0
	v_fma_f32 v17, -v27, v37, 1.0
	v_fmac_f32_e32 v37, v17, v37
	v_div_scale_f32 v17, vcc, 1.0, v25, 1.0
	v_mul_f32_e32 v19, v17, v37
	v_fma_f32 v21, -v27, v19, v17
	v_fmac_f32_e32 v19, v21, v37
	v_fma_f32 v17, -v27, v19, v17
	v_div_fmas_f32 v17, v17, v37, v19
	v_div_fixup_f32 v82, v17, v25, 1.0
	s_waitcnt vmcnt(11)
	v_pk_fma_f32 v[14:15], v[16:17], v[38:39], v[14:15] op_sel_hi:[0,1,1]
	s_waitcnt vmcnt(10)
	v_pk_fma_f32 v[14:15], v[18:19], v[40:41], v[14:15] op_sel_hi:[0,1,1]
	s_waitcnt vmcnt(9)
	v_pk_fma_f32 v[14:15], v[20:21], v[42:43], v[14:15] op_sel_hi:[0,1,1]
	s_waitcnt vmcnt(8)
	v_pk_fma_f32 v[14:15], v[22:23], v[12:13], v[14:15] op_sel_hi:[0,1,1]
	s_waitcnt vmcnt(7)
	v_pk_fma_f32 v[16:17], v[24:25], v[56:57], 0 op_sel_hi:[0,1,0]
	s_waitcnt vmcnt(6)
	v_pk_fma_f32 v[16:17], v[26:27], v[58:59], v[16:17] op_sel_hi:[0,1,1]
	s_waitcnt vmcnt(5)
	v_pk_fma_f32 v[16:17], v[44:45], v[60:61], v[16:17] op_sel_hi:[0,1,1]
	s_waitcnt vmcnt(4)
	v_pk_fma_f32 v[16:17], v[46:47], v[62:63], v[16:17] op_sel_hi:[0,1,1]
	s_waitcnt vmcnt(3)
	v_pk_fma_f32 v[16:17], v[48:49], v[64:65], v[16:17] op_sel_hi:[0,1,1]
	s_waitcnt vmcnt(2)
	v_pk_fma_f32 v[16:17], v[50:51], v[66:67], v[16:17] op_sel_hi:[0,1,1]
	s_waitcnt vmcnt(1)
	v_pk_fma_f32 v[16:17], v[52:53], v[68:69], v[16:17] op_sel_hi:[0,1,1]
	s_waitcnt vmcnt(0)
	v_pk_fma_f32 v[16:17], v[54:55], v[70:71], v[16:17] op_sel_hi:[0,1,1]
	v_pk_fma_f32 v[16:17], v[72:73], v[38:39], v[16:17] op_sel_hi:[0,1,1]
	v_pk_fma_f32 v[16:17], v[74:75], v[40:41], v[16:17] op_sel_hi:[0,1,1]
	v_pk_fma_f32 v[16:17], v[76:77], v[42:43], v[16:17] op_sel_hi:[0,1,1]
	v_pk_fma_f32 v[12:13], v[78:79], v[12:13], v[16:17] op_sel_hi:[0,1,1]
	v_pk_mul_f32 v[12:13], v[82:83], v[12:13] op_sel_hi:[0,1]
	v_pk_mul_f32 v[12:13], v[4:5], v[12:13]
	s_nop 0
	v_pk_fma_f32 v[12:13], v[80:81], v[14:15], v[12:13] op_sel_hi:[0,1,1] neg_lo:[0,0,1] neg_hi:[0,0,1]
	v_pk_mul_f32 v[14:15], v[12:13], v[12:13]
	s_nop 0
	v_add_f32_e32 v14, v14, v15
	s_nop 1
	v_add_f32_dpp v14, v14, v14 quad_perm:[1,0,3,2] row_mask:0xf bank_mask:0xf bound_ctrl:1
	s_nop 1
	v_add_f32_dpp v14, v14, v14 quad_perm:[2,3,0,1] row_mask:0xf bank_mask:0xf bound_ctrl:1
	s_nop 1
	v_add_f32_dpp v14, v14, v14 row_half_mirror row_mask:0xf bank_mask:0xf bound_ctrl:1
	s_nop 1
	v_add_f32_dpp v14, v14, v14 row_ror:8 row_mask:0xf bank_mask:0xf bound_ctrl:1
	v_mov_b32_e32 v15, v14
	s_nop 1
	v_permlane16_swap_b32_e32 v14, v15
	v_add_f32_e32 v14, v14, v15
	v_mov_b32_e32 v15, v14
	s_nop 1
	v_permlane32_swap_b32_e32 v14, v15
	v_add_f32_e32 v14, v14, v15
	v_fmamk_f32 v14, v14, 0x3c000000, v32
	v_mul_f32_e32 v15, 0x4f800000, v14
	v_cmp_gt_f32_e32 vcc, s30, v14
	s_nop 1
	v_cndmask_b32_e32 v14, v14, v15, vcc
	v_sqrt_f32_e32 v15, v14
	s_nop 0
	v_add_u32_e32 v16, -1, v15
	v_fma_f32 v17, -v16, v15, v14
	v_cmp_ge_f32_e64 s[12:13], 0, v17
	v_add_u32_e32 v17, 1, v15
	s_nop 0
	v_cndmask_b32_e64 v16, v15, v16, s[12:13]
	v_fma_f32 v15, -v17, v15, v14
	v_cmp_lt_f32_e64 s[12:13], 0, v15
	s_nop 1
	v_cndmask_b32_e64 v15, v16, v17, s[12:13]
	v_mul_f32_e32 v16, 0x37800000, v15
	v_cndmask_b32_e32 v15, v15, v16, vcc
	v_cmp_class_f32_e32 vcc, v14, v33
	s_nop 1
	v_cndmask_b32_e32 v14, v15, v14, vcc
	v_div_scale_f32 v15, s[12:13], v14, v14, s31
	v_rcp_f32_e32 v16, v15
	s_add_i32 s12, s16, 0x4000
	s_ashr_i32 s13, s12, 31
	s_lshl_b64 s[12:13], s[12:13], 11
	v_fma_f32 v17, -v15, v16, 1.0
	v_fmac_f32_e32 v16, v17, v16
	v_div_scale_f32 v17, vcc, s31, v14, s31
	v_mul_f32_e32 v18, v17, v16
	v_fma_f32 v19, -v15, v18, v17
	v_fmac_f32_e32 v18, v19, v16
	v_fma_f32 v15, -v15, v18, v17
	v_div_fmas_f32 v15, v15, v16, v18
	v_div_fixup_f32 v14, v15, v14, s31
	v_pk_mul_f32 v[12:13], v[12:13], v[14:15] op_sel_hi:[1,0]
	s_add_u32 s12, s26, s12
	v_pk_mul_f32 v[12:13], v[2:3], v[12:13]
	s_addc_u32 s13, s27, s13
	v_and_b32_sdwa v15, v12, v36 dst_sel:DWORD dst_unused:UNUSED_PAD src0_sel:WORD_1 src1_sel:DWORD
	s_lshl_b32 s16, s76, 8
	v_and_b32_sdwa v14, v13, v36 dst_sel:DWORD dst_unused:UNUSED_PAD src0_sel:WORD_1 src1_sel:DWORD
	v_add3_u32 v12, v12, v15, s41
	s_add_u32 s12, s12, s16
	v_add3_u32 v13, v13, v14, s41
	v_lshrrev_b32_e32 v12, 16, v12
	s_addc_u32 s13, s13, 0
	s_add_i32 s75, s75, s34
	v_and_or_b32 v12, v13, s72, v12
	v_lshlrev_b32_e32 v13, 1, v8
	s_cmpk_gt_i32 s75, 0x1ff
	global_store_dword v13, v12, s[12:13] sc1
	s_cbranch_scc1 .LBB0_657

.LBB0_657:
	s_waitcnt vmcnt(0)
	s_and_b64 vcc, exec, s[94:95]
	s_barrier
	s_cbranch_vccnz .LBB0_662
	v_mbcnt_lo_u32_b32 v0, -1, 0
	v_mbcnt_hi_u32_b32 v0, -1, v0
	s_nop 0
	v_cmp_eq_u32_e32 vcc, 0, v0
	s_and_saveexec_b64 s[6:7], vcc
	s_cbranch_execz .LBB0_661
	s_mov_b64 s[8:9], exec
	v_mbcnt_lo_u32_b32 v0, s8, 0
	s_waitcnt vmcnt(0)
	s_waitcnt vmcnt(0)
	v_mbcnt_hi_u32_b32 v0, s9, v0
	v_cmp_eq_u32_e32 vcc, 0, v0
	s_and_b64 s[10:11], exec, vcc
	s_mov_b64 exec, s[10:11]
	s_cbranch_execz .LBB0_661
	s_bcnt1_i32_b64 s8, s[8:9]
	v_mov_b32_e32 v0, 0
	v_mov_b32_e32 v1, s8
	global_atomic_add v0, v1, s[42:43]

.LBB0_716:
	s_waitcnt vmcnt(0) lgkmcnt(0)
.LBB0_717:
	s_waitcnt vmcnt(0) lgkmcnt(0)
	s_barrier
	v_lshl_add_u32 v211, v194, 2, 0
	s_and_saveexec_b64 s[52:53], s[10:11]
	s_cbranch_execz .LBB0_719
	v_lshlrev_b64 v[192:193], 5, v[202:203]
	v_lshl_add_u64 v[192:193], s[16:17], 0, v[192:193]
	global_load_dwordx2 v[194:195], v[192:193], off sc1
	global_load_dwordx2 v[196:197], v[192:193], off offset:8 sc1
	global_load_dwordx2 v[198:199], v[192:193], off offset:16 sc1
	s_nop 0
	global_load_dwordx2 v[192:193], v[192:193], off offset:24 sc1
	s_waitcnt vmcnt(0)
	v_mov_b32_e32 v193, 0x358637bd
	s_mov_b32 s16, 0xf800000
	v_add_f32_e32 v194, 0, v194
	v_add_f32_e32 v194, v194, v196
	v_add_f32_e32 v194, v194, v198
	v_add_f32_e32 v192, v194, v192
	v_fmac_f32_e32 v193, 0x3a800000, v192
	v_mul_f32_e32 v192, 0x4f800000, v193
	v_cmp_gt_f32_e32 vcc, s16, v193
	v_mov_b32_e32 v194, 0x260
	s_nop 0
	v_cndmask_b32_e32 v192, v193, v192, vcc
	v_sqrt_f32_e32 v193, v192
	s_nop 0
	v_add_u32_e32 v195, -1, v193
	v_add_u32_e32 v196, 1, v193
	v_fma_f32 v197, -v195, v193, v192
	v_fma_f32 v198, -v196, v193, v192
	v_cmp_ge_f32_e64 s[16:17], 0, v197
	s_nop 1
	v_cndmask_b32_e64 v193, v193, v195, s[16:17]
	v_cmp_lt_f32_e64 s[16:17], 0, v198
	s_nop 1
	v_cndmask_b32_e64 v193, v193, v196, s[16:17]
	v_mul_f32_e32 v195, 0x37800000, v193
	v_cndmask_b32_e32 v193, v193, v195, vcc
	v_cmp_class_f32_e32 vcc, v192, v194
	s_nop 1
	v_cndmask_b32_e32 v192, v193, v192, vcc
	v_div_scale_f32 v193, s[16:17], v192, v192, 1.0
	v_rcp_f32_e32 v194, v193
	v_div_scale_f32 v195, vcc, 1.0, v192, 1.0
	v_fma_f32 v196, -v193, v194, 1.0
	v_fmac_f32_e32 v194, v196, v194
	v_mul_f32_e32 v196, v195, v194
	v_fma_f32 v197, -v193, v196, v195
	v_fmac_f32_e32 v196, v197, v194
	v_fma_f32 v193, -v193, v196, v195
	v_div_fmas_f32 v193, v193, v194, v196
	v_div_fixup_f32 v192, v193, v192, 1.0
	ds_write_b32 v211, v192 offset:8192

.LBB0_751:
	s_waitcnt vmcnt(0) lgkmcnt(0)
.LBB0_752:
	s_waitcnt vmcnt(0) lgkmcnt(0)
	s_barrier
	s_and_saveexec_b64 s[12:13], s[10:11]
	s_cbranch_execz .LBB0_754
	v_lshlrev_b64 v[128:129], 5, v[202:203]
	v_lshl_add_u64 v[128:129], s[8:9], 0, v[128:129]
	global_load_dwordx2 v[130:131], v[128:129], off sc1
	global_load_dwordx2 v[132:133], v[128:129], off offset:8 sc1
	global_load_dwordx2 v[134:135], v[128:129], off offset:16 sc1
	s_nop 0
	global_load_dwordx2 v[128:129], v[128:129], off offset:24 sc1
	s_waitcnt vmcnt(0)
	v_mov_b32_e32 v129, 0x358637bd
	s_mov_b32 s8, 0xf800000
	v_add_f32_e32 v130, 0, v130
	v_add_f32_e32 v130, v130, v132
	v_add_f32_e32 v130, v130, v134
	v_add_f32_e32 v128, v130, v128
	v_fmac_f32_e32 v129, 0x3a800000, v128
	v_mul_f32_e32 v128, 0x4f800000, v129
	v_cmp_gt_f32_e32 vcc, s8, v129
	v_mov_b32_e32 v130, 0x260
	s_nop 0
	v_cndmask_b32_e32 v128, v129, v128, vcc
	v_sqrt_f32_e32 v129, v128
	s_nop 0
	v_add_u32_e32 v131, -1, v129
	v_add_u32_e32 v132, 1, v129
	v_fma_f32 v133, -v131, v129, v128
	v_fma_f32 v134, -v132, v129, v128
	v_cmp_ge_f32_e64 s[8:9], 0, v133
	s_nop 1
	v_cndmask_b32_e64 v129, v129, v131, s[8:9]
	v_cmp_lt_f32_e64 s[8:9], 0, v134
	s_nop 1
	v_cndmask_b32_e64 v129, v129, v132, s[8:9]
	v_mul_f32_e32 v131, 0x37800000, v129
	v_cndmask_b32_e32 v129, v129, v131, vcc
	v_cmp_class_f32_e32 vcc, v128, v130
	s_nop 1
	v_cndmask_b32_e32 v128, v129, v128, vcc
	v_div_scale_f32 v129, s[8:9], v128, v128, 1.0
	v_rcp_f32_e32 v130, v129
	v_div_scale_f32 v131, vcc, 1.0, v128, 1.0
	v_fma_f32 v132, -v129, v130, 1.0
	v_fmac_f32_e32 v130, v132, v130
	v_mul_f32_e32 v132, v131, v130
	v_fma_f32 v133, -v129, v132, v131
	v_fmac_f32_e32 v132, v133, v130
	v_fma_f32 v129, -v129, v132, v131
	v_div_fmas_f32 v129, v129, v130, v132
	v_div_fixup_f32 v128, v129, v128, 1.0
	ds_write_b32 v211, v128 offset:8192

.LBB0_832:
	v_lshl_add_u64 v[18:19], s[12:13], 0, v[12:13]
	v_add_co_u32_e32 v58, vcc, s14, v18
	v_lshl_add_u64 v[20:21], s[12:13], 0, v[16:17]
	s_nop 0
	v_addc_co_u32_e32 v59, vcc, 0, v19, vcc
	v_add_co_u32_e32 v62, vcc, s15, v18
	v_lshl_add_u64 v[34:35], s[12:13], 0, v[14:15]
	s_nop 0
	v_addc_co_u32_e32 v63, vcc, 0, v19, vcc
	s_waitcnt vmcnt(14)
	v_add_co_u32_e32 v78, vcc, s24, v18
	global_load_dwordx4 v[0:3], v[8:9], off
	global_load_dwordx4 v[4:7], v[8:9], off offset:1024
	global_load_dwordx4 v[26:29], v[8:9], off offset:2048
	global_load_dwordx4 v[30:33], v[8:9], off offset:3072
	v_addc_co_u32_e32 v79, vcc, 0, v19, vcc
	s_waitcnt vmcnt(14)
	v_add_co_u32_e32 v94, vcc, s25, v18
	s_add_i32 s8, s40, 0x4000
	s_nop 0
	v_addc_co_u32_e32 v95, vcc, 0, v19, vcc
	v_add_co_u32_e32 v20, vcc, s27, v20
	s_cmpk_lt_i32 s8, 0x4000
	s_nop 0
	v_addc_co_u32_e32 v21, vcc, 0, v21, vcc
	v_add_co_u32_e32 v18, vcc, s30, v34
	s_cselect_b32 s9, s43, 0
	s_nop 0
	v_addc_co_u32_e32 v19, vcc, 0, v35, vcc
	global_load_dwordx4 v[34:37], v[62:63], off
	global_load_dwordx4 v[38:41], v[58:59], off
	global_load_dwordx4 v[42:45], v[58:59], off offset:1024
	global_load_dwordx4 v[46:49], v[62:63], off offset:1024
	global_load_dwordx4 v[50:53], v[62:63], off offset:2048
	global_load_dwordx4 v[54:57], v[58:59], off offset:2048
	s_nop 0
	global_load_dwordx4 v[58:61], v[58:59], off offset:3072
	s_nop 0
	global_load_dwordx4 v[62:65], v[62:63], off offset:3072
	s_nop 0
	global_load_dwordx4 v[66:69], v[78:79], off
	global_load_dwordx4 v[70:73], v[78:79], off offset:1024
	global_load_dwordx4 v[74:77], v[78:79], off offset:2048
	s_nop 0
	global_load_dwordx4 v[78:81], v[78:79], off offset:3072
	s_nop 0
	global_load_dwordx4 v[82:85], v[94:95], off
	global_load_dwordx4 v[86:89], v[94:95], off offset:1024
	global_load_dwordx4 v[90:93], v[94:95], off offset:2048
	s_nop 0
	global_load_dwordx4 v[94:97], v[94:95], off offset:3072
	s_cselect_b32 s8, s42, s40
	s_cselect_b32 s31, s17, s19
	s_cselect_b32 s41, s16, s18
	s_lshl_b64 s[8:9], s[8:9], 12
	s_add_u32 s8, s41, s8
	s_addc_u32 s9, s31, s9
	global_load_dwordx4 v[98:101], v22, s[8:9]
	global_load_dwordx4 v[102:105], v22, s[8:9] offset:1024
	global_load_dwordx4 v[106:109], v22, s[8:9] offset:2048
	global_load_dwordx4 v[110:113], v22, s[8:9] offset:3072
	s_add_i32 s40, s40, s34
	v_lshl_add_u64 v[12:13], v[12:13], 0, s[44:45]
	v_lshl_add_u64 v[14:15], v[14:15], 0, s[46:47]
	v_lshl_add_u64 v[16:17], v[16:17], 0, s[44:45]
	s_waitcnt vmcnt(18)
	v_pk_add_f32 v[36:37], v[40:41], v[36:37]
	v_pk_add_f32 v[34:35], v[38:39], v[34:35]
	s_waitcnt vmcnt(16)
	v_pk_add_f32 v[38:39], v[44:45], v[48:49]
	v_pk_add_f32 v[40:41], v[42:43], v[46:47]
	s_waitcnt vmcnt(14)
	v_pk_add_f32 v[42:43], v[56:57], v[52:53]
	v_pk_add_f32 v[44:45], v[54:55], v[50:51]
	s_waitcnt vmcnt(12)
	v_pk_add_f32 v[46:47], v[60:61], v[64:65]
	s_waitcnt vmcnt(11)
	v_pk_add_f32 v[36:37], v[36:37], v[68:69]
	v_pk_add_f32 v[34:35], v[34:35], v[66:67]
	s_waitcnt vmcnt(10)
	v_pk_add_f32 v[38:39], v[38:39], v[72:73]
	v_pk_add_f32 v[40:41], v[40:41], v[70:71]
	v_pk_add_f32 v[48:49], v[58:59], v[62:63]
	s_waitcnt vmcnt(9)
	v_pk_add_f32 v[42:43], v[42:43], v[76:77]
	v_pk_add_f32 v[44:45], v[44:45], v[74:75]
	s_waitcnt vmcnt(7)
	v_pk_add_f32 v[36:37], v[36:37], v[84:85]
	v_pk_add_f32 v[34:35], v[34:35], v[82:83]
	s_waitcnt vmcnt(6)
	v_pk_add_f32 v[38:39], v[38:39], v[88:89]
	v_pk_add_f32 v[40:41], v[40:41], v[86:87]
	v_pk_add_f32 v[46:47], v[46:47], v[80:81]
	v_pk_add_f32 v[48:49], v[48:49], v[78:79]
	s_waitcnt vmcnt(5)
	v_pk_add_f32 v[42:43], v[42:43], v[92:93]
	v_pk_add_f32 v[44:45], v[44:45], v[90:91]
	v_mul_f32_e32 v25, v35, v35
	v_mul_f32_e32 v50, v37, v37
	v_mul_f32_e32 v51, v41, v41
	v_mul_f32_e32 v52, v39, v39
	s_waitcnt vmcnt(4)
	v_pk_add_f32 v[46:47], v[46:47], v[96:97]
	v_pk_add_f32 v[48:49], v[48:49], v[94:95]
	v_mul_f32_e32 v53, v45, v45
	v_mul_f32_e32 v54, v43, v43
	v_fmac_f32_e32 v25, v34, v34
	v_fmac_f32_e32 v50, v36, v36
	v_fmac_f32_e32 v51, v40, v40
	v_fmac_f32_e32 v52, v38, v38
	v_mul_f32_e32 v55, v49, v49
	v_mul_f32_e32 v56, v47, v47
	v_fmac_f32_e32 v53, v44, v44
	v_fmac_f32_e32 v54, v42, v42
	v_add_f32_e32 v25, v25, v50
	v_add_f32_e32 v50, v51, v52
	v_fmac_f32_e32 v55, v48, v48
	v_fmac_f32_e32 v56, v46, v46
	v_add_f32_e32 v51, v53, v54
	v_add_f32_e32 v25, v25, v50
	v_add_f32_e32 v52, v55, v56
	v_add_f32_e32 v25, v25, v51
	v_add_f32_e32 v25, v25, v52
	s_nop 1
	v_add_f32_dpp v25, v25, v25 quad_perm:[1,0,3,2] row_mask:0xf bank_mask:0xf bound_ctrl:1
	s_nop 1
	v_add_f32_dpp v25, v25, v25 quad_perm:[2,3,0,1] row_mask:0xf bank_mask:0xf bound_ctrl:1
	s_nop 1
	v_add_f32_dpp v25, v25, v25 row_half_mirror row_mask:0xf bank_mask:0xf bound_ctrl:1
	s_nop 1
	v_add_f32_dpp v25, v25, v25 row_ror:8 row_mask:0xf bank_mask:0xf bound_ctrl:1
	v_mov_b32_e32 v50, v25
	s_nop 1
	v_permlane16_swap_b32_e32 v25, v50
	v_add_f32_e32 v25, v25, v50
	v_mov_b32_e32 v50, v25
	s_nop 1
	v_permlane32_swap_b32_e32 v25, v50
	v_add_f32_e32 v25, v25, v50
	v_fmamk_f32 v25, v25, 0x3a800000, v23
	v_mul_f32_e32 v50, 0x4f800000, v25
	v_cmp_gt_f32_e32 vcc, s26, v25
	s_nop 1
	v_cndmask_b32_e32 v25, v25, v50, vcc
	v_sqrt_f32_e32 v50, v25
	s_nop 0
	v_add_u32_e32 v51, -1, v50
	v_add_u32_e32 v52, 1, v50
	v_fma_f32 v53, -v51, v50, v25
	v_fma_f32 v54, -v52, v50, v25
	v_cmp_ge_f32_e64 s[8:9], 0, v53
	s_nop 1
	v_cndmask_b32_e64 v50, v50, v51, s[8:9]
	v_cmp_lt_f32_e64 s[8:9], 0, v54
	s_nop 1
	v_cndmask_b32_e64 v50, v50, v52, s[8:9]
	v_mul_f32_e32 v51, 0x37800000, v50
	v_cndmask_b32_e32 v50, v50, v51, vcc
	v_cmp_class_f32_e32 vcc, v25, v24
	s_nop 1
	v_cndmask_b32_e32 v25, v50, v25, vcc
	v_div_scale_f32 v50, s[8:9], v25, v25, 1.0
	v_rcp_f32_e32 v52, v50
	v_div_scale_f32 v51, vcc, 1.0, v25, 1.0
	v_fma_f32 v53, -v50, v52, 1.0
	v_fmac_f32_e32 v52, v53, v52
	v_mul_f32_e32 v53, v51, v52
	v_fma_f32 v54, -v50, v53, v51
	v_fmac_f32_e32 v53, v54, v52
	v_fma_f32 v50, -v50, v53, v51
	v_div_fmas_f32 v50, v50, v52, v53
	v_div_fixup_f32 v50, v50, v25, 1.0
	v_pk_mul_f32 v[34:35], v[34:35], v[50:51] op_sel_hi:[1,0]
	v_pk_mul_f32 v[36:37], v[36:37], v[50:51] op_sel_hi:[1,0]
	s_waitcnt vmcnt(3)
	v_pk_fma_f32 v[0:1], v[0:1], v[34:35], v[98:99]
	v_pk_fma_f32 v[2:3], v[2:3], v[36:37], v[100:101]
	global_store_dwordx4 v[20:21], v[0:3], off sc1
	global_load_dwordx4 v[34:37], v[10:11], off
	v_pk_mul_f32 v[40:41], v[40:41], v[50:51] op_sel_hi:[1,0]
	v_pk_mul_f32 v[38:39], v[38:39], v[50:51] op_sel_hi:[1,0]
	v_pk_mul_f32 v[44:45], v[44:45], v[50:51] op_sel_hi:[1,0]
	v_pk_mul_f32 v[42:43], v[42:43], v[50:51] op_sel_hi:[1,0]
	s_waitcnt vmcnt(4)
	v_pk_fma_f32 v[6:7], v[6:7], v[38:39], v[104:105]
	v_pk_fma_f32 v[4:5], v[4:5], v[40:41], v[102:103]
	v_pk_mul_f32 v[48:49], v[48:49], v[50:51] op_sel_hi:[1,0]
	v_pk_mul_f32 v[46:47], v[46:47], v[50:51] op_sel_hi:[1,0]
	s_waitcnt vmcnt(3)
	v_pk_fma_f32 v[28:29], v[28:29], v[42:43], v[108:109]
	v_pk_fma_f32 v[26:27], v[26:27], v[44:45], v[106:107]
	v_mul_f32_e32 v25, v1, v1
	v_mul_f32_e32 v38, v3, v3
	v_mul_f32_e32 v39, v5, v5
	v_mul_f32_e32 v40, v7, v7
	s_waitcnt vmcnt(2)
	v_pk_fma_f32 v[32:33], v[32:33], v[46:47], v[112:113]
	v_pk_fma_f32 v[30:31], v[30:31], v[48:49], v[110:111]
	v_mul_f32_e32 v41, v27, v27
	v_mul_f32_e32 v42, v29, v29
	v_fmac_f32_e32 v25, v0, v0
	v_fmac_f32_e32 v38, v2, v2
	v_fmac_f32_e32 v39, v4, v4
	v_fmac_f32_e32 v40, v6, v6
	v_mul_f32_e32 v43, v31, v31
	v_mul_f32_e32 v44, v33, v33
	v_fmac_f32_e32 v41, v26, v26
	v_fmac_f32_e32 v42, v28, v28
	v_add_f32_e32 v25, v25, v38
	v_add_f32_e32 v38, v39, v40
	v_fmac_f32_e32 v43, v30, v30
	v_fmac_f32_e32 v44, v32, v32
	v_add_f32_e32 v39, v41, v42
	v_add_f32_e32 v25, v25, v38
	v_add_f32_e32 v40, v43, v44
	v_add_f32_e32 v25, v39, v25
	v_add_f32_e32 v25, v40, v25
	s_nop 1
	v_add_f32_dpp v25, v25, v25 quad_perm:[1,0,3,2] row_mask:0xf bank_mask:0xf bound_ctrl:1
	s_nop 1
	v_add_f32_dpp v25, v25, v25 quad_perm:[2,3,0,1] row_mask:0xf bank_mask:0xf bound_ctrl:1
	s_nop 1
	v_add_f32_dpp v25, v25, v25 row_half_mirror row_mask:0xf bank_mask:0xf bound_ctrl:1
	s_nop 1
	v_add_f32_dpp v25, v25, v25 row_ror:8 row_mask:0xf bank_mask:0xf bound_ctrl:1
	v_mov_b32_e32 v38, v25
	s_nop 1
	v_permlane16_swap_b32_e32 v25, v38
	v_add_f32_e32 v25, v25, v38
	v_mov_b32_e32 v38, v25
	s_nop 1
	v_permlane32_swap_b32_e32 v25, v38
	v_add_f32_e32 v25, v25, v38
	v_fmamk_f32 v25, v25, 0x3a800000, v23
	v_mul_f32_e32 v38, 0x4f800000, v25
	v_cmp_gt_f32_e32 vcc, s26, v25
	s_nop 1
	v_cndmask_b32_e32 v25, v25, v38, vcc
	v_sqrt_f32_e32 v38, v25
	s_nop 0
	v_add_u32_e32 v39, -1, v38
	v_add_u32_e32 v40, 1, v38
	v_fma_f32 v41, -v39, v38, v25
	v_fma_f32 v42, -v40, v38, v25
	v_cmp_ge_f32_e64 s[8:9], 0, v41
	s_nop 1
	v_cndmask_b32_e64 v38, v38, v39, s[8:9]
	v_cmp_lt_f32_e64 s[8:9], 0, v42
	s_nop 1
	v_cndmask_b32_e64 v38, v38, v40, s[8:9]
	v_mul_f32_e32 v39, 0x37800000, v38
	v_cndmask_b32_e32 v38, v38, v39, vcc
	v_cmp_class_f32_e32 vcc, v25, v24
	s_nop 1
	v_cndmask_b32_e32 v25, v38, v25, vcc
	v_div_scale_f32 v38, s[8:9], v25, v25, 1.0
	v_rcp_f32_e32 v40, v38
	v_div_scale_f32 v39, vcc, 1.0, v25, 1.0
	s_add_i32 s8, s40, 0x4000
	v_fma_f32 v41, -v38, v40, 1.0
	v_fmac_f32_e32 v40, v41, v40
	v_mul_f32_e32 v41, v39, v40
	v_fma_f32 v42, -v38, v41, v39
	v_fmac_f32_e32 v41, v42, v40
	v_fma_f32 v38, -v38, v41, v39
	v_div_fmas_f32 v38, v38, v40, v41
	v_div_fixup_f32 v25, v38, v25, 1.0
	v_mul_f32_e32 v0, v0, v25
	v_mul_f32_e32 v2, v2, v25
	v_mul_f32_e32 v1, v1, v25
	v_mul_f32_e32 v3, v3, v25
	s_waitcnt vmcnt(0)
	v_mul_f32_e32 v0, v34, v0
	v_mul_f32_e32 v2, v36, v2
	v_mul_f32_e32 v1, v35, v1
	v_mul_f32_e32 v3, v37, v3
	v_bfe_u32 v34, v0, 16, 1
	v_bfe_u32 v36, v2, 16, 1
	v_bfe_u32 v35, v1, 16, 1
	v_bfe_u32 v37, v3, 16, 1
	v_add3_u32 v0, v0, v34, s28
	v_add3_u32 v2, v2, v36, s28
	v_add3_u32 v1, v1, v35, s28
	v_add3_u32 v3, v3, v37, s28
	v_lshrrev_b32_e32 v0, 16, v0
	v_lshrrev_b32_e32 v2, 16, v2
	v_and_or_b32 v0, v1, s29, v0
	v_and_or_b32 v1, v3, s29, v2
	global_store_dwordx2 v[18:19], v[0:1], off sc1
	global_store_dwordx4 v[20:21], v[4:7], off offset:1024 sc1
	global_load_dwordx4 v[0:3], v[10:11], off offset:1024
	s_add_u32 s42, s42, s34
	v_mul_f32_e32 v4, v4, v25
	v_mul_f32_e32 v6, v6, v25
	v_mul_f32_e32 v5, v5, v25
	v_mul_f32_e32 v7, v7, v25
	s_addc_u32 s43, s43, s35
	s_cmpk_gt_i32 s8, 0x407f
	s_waitcnt vmcnt(0)
	v_mul_f32_e32 v0, v0, v4
	v_mul_f32_e32 v2, v2, v6
	v_mul_f32_e32 v1, v1, v5
	v_mul_f32_e32 v3, v3, v7
	v_bfe_u32 v4, v0, 16, 1
	v_bfe_u32 v6, v2, 16, 1
	v_bfe_u32 v5, v1, 16, 1
	v_bfe_u32 v7, v3, 16, 1
	v_add3_u32 v0, v0, v4, s28
	v_add3_u32 v2, v2, v6, s28
	v_add3_u32 v1, v1, v5, s28
	v_add3_u32 v3, v3, v7, s28
	v_lshrrev_b32_e32 v0, 16, v0
	v_lshrrev_b32_e32 v2, 16, v2
	v_and_or_b32 v0, v1, s29, v0
	v_and_or_b32 v1, v3, s29, v2
	global_store_dwordx2 v[18:19], v[0:1], off offset:512 sc1
	global_store_dwordx4 v[20:21], v[26:29], off offset:2048 sc1
	global_load_dwordx4 v[0:3], v[10:11], off offset:2048
	v_mul_f32_e32 v4, v26, v25
	v_mul_f32_e32 v6, v28, v25
	v_mul_f32_e32 v5, v27, v25
	v_mul_f32_e32 v7, v29, v25
	s_waitcnt vmcnt(0)
	v_mul_f32_e32 v0, v4, v0
	v_mul_f32_e32 v2, v6, v2
	v_mul_f32_e32 v1, v5, v1
	v_mul_f32_e32 v3, v7, v3
	v_bfe_u32 v4, v0, 16, 1
	v_bfe_u32 v6, v2, 16, 1
	v_bfe_u32 v5, v1, 16, 1
	v_bfe_u32 v7, v3, 16, 1
	v_add3_u32 v0, v0, v4, s28
	v_add3_u32 v2, v2, v6, s28
	v_add3_u32 v1, v1, v5, s28
	v_add3_u32 v3, v3, v7, s28
	v_lshrrev_b32_e32 v0, 16, v0
	v_lshrrev_b32_e32 v2, 16, v2
	v_and_or_b32 v0, v1, s29, v0
	v_and_or_b32 v1, v3, s29, v2
	global_store_dwordx2 v[18:19], v[0:1], off offset:1024 sc1
	global_store_dwordx4 v[20:21], v[30:33], off offset:3072 sc1
	global_load_dwordx4 v[0:3], v[10:11], off offset:3072
	v_mul_f32_e32 v4, v30, v25
	v_mul_f32_e32 v6, v32, v25
	v_mul_f32_e32 v5, v31, v25
	v_mul_f32_e32 v7, v33, v25
	s_waitcnt vmcnt(0)
	v_mul_f32_e32 v0, v4, v0
	v_mul_f32_e32 v2, v6, v2
	v_mul_f32_e32 v1, v5, v1
	v_mul_f32_e32 v3, v7, v3
	v_bfe_u32 v4, v0, 16, 1
	v_bfe_u32 v6, v2, 16, 1
	v_bfe_u32 v5, v1, 16, 1
	v_bfe_u32 v7, v3, 16, 1
	v_add3_u32 v0, v0, v4, s28
	v_add3_u32 v2, v2, v6, s28
	v_add3_u32 v1, v1, v5, s28
	v_add3_u32 v3, v3, v7, s28
	v_lshrrev_b32_e32 v0, 16, v0
	v_lshrrev_b32_e32 v2, 16, v2
	v_and_or_b32 v0, v1, s29, v0
	v_and_or_b32 v1, v3, s29, v2
	global_store_dwordx2 v[18:19], v[0:1], off offset:1536 sc1
	s_cbranch_scc0 .LBB0_832
.LBB0_833:
	s_waitcnt vmcnt(0)
	s_and_b64 vcc, exec, s[94:95]
	s_waitcnt lgkmcnt(0)
	s_barrier
	s_cbranch_vccnz .LBB0_838
	v_mbcnt_lo_u32_b32 v0, -1, 0
	v_mbcnt_hi_u32_b32 v0, -1, v0
	s_nop 0
	v_cmp_eq_u32_e32 vcc, 0, v0
	s_and_saveexec_b64 s[8:9], vcc
	s_cbranch_execz .LBB0_837
	s_mov_b64 s[16:17], exec
	v_mbcnt_lo_u32_b32 v0, s16, 0
	s_waitcnt vmcnt(0)
	s_waitcnt vmcnt(0)
	v_mbcnt_hi_u32_b32 v0, s17, v0
	v_cmp_eq_u32_e32 vcc, 0, v0
	s_and_b64 s[14:15], exec, vcc
	s_mov_b64 exec, s[14:15]
	s_cbranch_execz .LBB0_837
	s_bcnt1_i32_b64 s14, s[16:17]
	v_mov_b32_e32 v0, 0
	v_mov_b32_e32 v1, s14
	global_atomic_add v0, v1, s[22:23]

.LBB0_997:
	s_waitcnt vmcnt(0) lgkmcnt(0)
.LBB0_998:
	s_waitcnt vmcnt(0) lgkmcnt(0)
	s_barrier
	s_and_saveexec_b64 s[10:11], s[8:9]
	s_cbranch_execz .LBB0_1000
	v_lshlrev_b64 v[192:193], 5, v[192:193]
	v_lshl_add_u64 v[192:193], s[12:13], 0, v[192:193]
	global_load_dwordx2 v[194:195], v[192:193], off sc1
	global_load_dwordx2 v[198:199], v[192:193], off offset:8 sc1
	global_load_dwordx2 v[202:203], v[192:193], off offset:16 sc1
	s_nop 0
	global_load_dwordx2 v[192:193], v[192:193], off offset:24 sc1
	s_waitcnt vmcnt(0)
	v_mov_b32_e32 v193, 0x358637bd
	s_mov_b32 s8, 0xf800000
	v_add_f32_e32 v194, 0, v194
	v_add_f32_e32 v194, v194, v198
	v_add_f32_e32 v194, v194, v202
	v_add_f32_e32 v192, v194, v192
	v_fmac_f32_e32 v193, 0x3a800000, v192
	v_mul_f32_e32 v192, 0x4f800000, v193
	v_cmp_gt_f32_e32 vcc, s8, v193
	v_mov_b32_e32 v194, 0x260
	s_nop 0
	v_cndmask_b32_e32 v192, v193, v192, vcc
	v_sqrt_f32_e32 v193, v192
	s_nop 0
	v_add_u32_e32 v195, -1, v193
	v_add_u32_e32 v197, 1, v193
	v_fma_f32 v198, -v195, v193, v192
	v_fma_f32 v199, -v197, v193, v192
	v_cmp_ge_f32_e64 s[8:9], 0, v198
	s_nop 1
	v_cndmask_b32_e64 v193, v193, v195, s[8:9]
	v_cmp_lt_f32_e64 s[8:9], 0, v199
	s_nop 1
	v_cndmask_b32_e64 v193, v193, v197, s[8:9]
	v_mul_f32_e32 v195, 0x37800000, v193
	v_cndmask_b32_e32 v193, v193, v195, vcc
	v_cmp_class_f32_e32 vcc, v192, v194
	s_nop 1
	v_cndmask_b32_e32 v192, v193, v192, vcc
	v_div_scale_f32 v193, s[8:9], v192, v192, 1.0
	v_rcp_f32_e32 v194, v193
	v_div_scale_f32 v195, vcc, 1.0, v192, 1.0
	v_fma_f32 v197, -v193, v194, 1.0
	v_fmac_f32_e32 v194, v197, v194
	v_mul_f32_e32 v197, v195, v194
	v_fma_f32 v198, -v193, v197, v195
	v_fmac_f32_e32 v197, v198, v194
	v_fma_f32 v193, -v193, v197, v195
	v_div_fmas_f32 v193, v193, v194, v197
	v_div_fixup_f32 v192, v193, v192, 1.0
	v_lshl_add_u32 v193, v196, 2, 0
	ds_write_b32 v193, v192 offset:8192

.LBB0_1062:
	v_lshl_add_u64 v[70:71], s[10:11], 0, v[6:7]
	v_add_co_u32_e32 v46, vcc, 0x29900000, v70
	v_lshl_add_u64 v[8:9], s[10:11], 0, v[4:5]
	s_nop 0
	v_addc_co_u32_e32 v47, vcc, 0, v71, vcc
	v_add_co_u32_e64 v86, s[4:5], s1, v8
	v_add_co_u32_e32 v54, vcc, 0x29980000, v70
	s_nop 0
	v_addc_co_u32_e64 v87, s[4:5], 0, v9, s[4:5]
	v_addc_co_u32_e32 v55, vcc, 0, v71, vcc
	global_load_dwordx4 v[14:17], v[0:1], off
	global_load_dwordx4 v[18:21], v[86:87], off
	v_add_co_u32_e32 v72, vcc, 0x29a00000, v70
	global_load_dwordx4 v[22:25], v[46:47], off
	global_load_dwordx4 v[26:29], v[46:47], off offset:1024
	global_load_dwordx4 v[30:33], v[46:47], off offset:2048
	global_load_dwordx4 v[34:37], v[46:47], off offset:3072
	global_load_dwordx4 v[38:41], v[54:55], off
	global_load_dwordx4 v[42:45], v[54:55], off offset:1024
	v_addc_co_u32_e32 v73, vcc, 0, v71, vcc
	global_load_dwordx4 v[46:49], v[54:55], off offset:2048
	global_load_dwordx4 v[50:53], v[54:55], off offset:3072
	v_add_co_u32_e32 v88, vcc, 0x29a80000, v70
	global_load_dwordx4 v[54:57], v[72:73], off
	global_load_dwordx4 v[58:61], v[72:73], off offset:1024
	global_load_dwordx4 v[62:65], v[72:73], off offset:2048
	global_load_dwordx4 v[66:69], v[72:73], off offset:3072
	v_addc_co_u32_e32 v89, vcc, 0, v71, vcc
	global_load_dwordx4 v[70:73], v[88:89], off
	global_load_dwordx4 v[74:77], v[88:89], off offset:1024
	global_load_dwordx4 v[78:81], v[88:89], off offset:2048
	global_load_dwordx4 v[82:85], v[88:89], off offset:3072
	v_add_co_u32_e64 v8, s[4:5], s15, v8
	v_lshl_add_u64 v[10:11], s[10:11], 0, v[2:3]
	s_nop 0
	v_addc_co_u32_e64 v9, s[4:5], 0, v9, s[4:5]
	v_add_co_u32_e64 v10, s[4:5], s26, v10
	s_add_i32 s16, s16, s18
	s_nop 0
	v_addc_co_u32_e64 v11, s[4:5], 0, v11, s[4:5]
	v_lshl_add_u64 v[2:3], v[2:3], 0, s[22:23]
	v_lshl_add_u64 v[4:5], v[4:5], 0, s[24:25]
	v_lshl_add_u64 v[6:7], v[6:7], 0, s[24:25]
	s_cmpk_gt_i32 s16, 0x407f
	s_waitcnt vmcnt(11)
	v_pk_add_f32 v[24:25], v[24:25], v[40:41]
	v_pk_add_f32 v[22:23], v[22:23], v[38:39]
	s_waitcnt vmcnt(10)
	v_pk_add_f32 v[28:29], v[28:29], v[44:45]
	v_pk_add_f32 v[26:27], v[26:27], v[42:43]
	s_waitcnt vmcnt(9)
	v_pk_add_f32 v[32:33], v[32:33], v[48:49]
	v_pk_add_f32 v[30:31], v[30:31], v[46:47]
	s_waitcnt vmcnt(7)
	v_pk_add_f32 v[24:25], v[24:25], v[56:57]
	v_pk_add_f32 v[22:23], v[22:23], v[54:55]
	s_waitcnt vmcnt(6)
	v_pk_add_f32 v[28:29], v[28:29], v[60:61]
	v_pk_add_f32 v[26:27], v[26:27], v[58:59]
	v_pk_add_f32 v[36:37], v[36:37], v[52:53]
	v_pk_add_f32 v[34:35], v[34:35], v[50:51]
	s_waitcnt vmcnt(5)
	v_pk_add_f32 v[32:33], v[32:33], v[64:65]
	v_pk_add_f32 v[30:31], v[30:31], v[62:63]
	s_waitcnt vmcnt(3)
	v_pk_add_f32 v[24:25], v[24:25], v[72:73]
	v_pk_add_f32 v[22:23], v[22:23], v[70:71]
	s_waitcnt vmcnt(2)
	v_pk_add_f32 v[28:29], v[28:29], v[76:77]
	v_pk_add_f32 v[26:27], v[26:27], v[74:75]
	v_pk_add_f32 v[36:37], v[36:37], v[68:69]
	v_pk_add_f32 v[34:35], v[34:35], v[66:67]
	s_waitcnt vmcnt(1)
	v_pk_add_f32 v[32:33], v[32:33], v[80:81]
	v_pk_add_f32 v[30:31], v[30:31], v[78:79]
	v_mul_f32_e32 v38, v23, v23
	v_mul_f32_e32 v39, v25, v25
	v_mul_f32_e32 v40, v27, v27
	v_mul_f32_e32 v41, v29, v29
	s_waitcnt vmcnt(0)
	v_pk_add_f32 v[36:37], v[36:37], v[84:85]
	v_pk_add_f32 v[34:35], v[34:35], v[82:83]
	v_mul_f32_e32 v42, v31, v31
	v_mul_f32_e32 v43, v33, v33
	v_fmac_f32_e32 v38, v22, v22
	v_fmac_f32_e32 v39, v24, v24
	v_fmac_f32_e32 v40, v26, v26
	v_fmac_f32_e32 v41, v28, v28
	v_mul_f32_e32 v44, v35, v35
	v_mul_f32_e32 v45, v37, v37
	v_fmac_f32_e32 v42, v30, v30
	v_fmac_f32_e32 v43, v32, v32
	v_add_f32_e32 v38, v38, v39
	v_add_f32_e32 v39, v40, v41
	v_fmac_f32_e32 v44, v34, v34
	v_fmac_f32_e32 v45, v36, v36
	v_add_f32_e32 v40, v42, v43
	v_add_f32_e32 v38, v38, v39
	v_add_f32_e32 v41, v44, v45
	v_add_f32_e32 v38, v38, v40
	v_add_f32_e32 v38, v38, v41
	s_nop 1
	v_add_f32_dpp v38, v38, v38 quad_perm:[1,0,3,2] row_mask:0xf bank_mask:0xf bound_ctrl:1
	s_nop 1
	v_add_f32_dpp v38, v38, v38 quad_perm:[2,3,0,1] row_mask:0xf bank_mask:0xf bound_ctrl:1
	s_nop 1
	v_add_f32_dpp v38, v38, v38 row_half_mirror row_mask:0xf bank_mask:0xf bound_ctrl:1
	s_nop 1
	v_add_f32_dpp v38, v38, v38 row_ror:8 row_mask:0xf bank_mask:0xf bound_ctrl:1
	v_mov_b32_e32 v39, v38
	s_nop 1
	v_permlane16_swap_b32_e32 v38, v39
	v_add_f32_e32 v38, v38, v39
	v_mov_b32_e32 v39, v38
	s_nop 1
	v_permlane32_swap_b32_e32 v38, v39
	v_add_f32_e32 v38, v38, v39
	v_fmamk_f32 v38, v38, 0x3a800000, v12
	v_mul_f32_e32 v39, 0x4f800000, v38
	v_cmp_gt_f32_e32 vcc, s0, v38
	s_nop 1
	v_cndmask_b32_e32 v38, v38, v39, vcc
	v_sqrt_f32_e32 v39, v38
	s_nop 0
	v_add_u32_e32 v40, -1, v39
	v_add_u32_e32 v41, 1, v39
	v_fma_f32 v42, -v40, v39, v38
	v_fma_f32 v43, -v41, v39, v38
	v_cmp_ge_f32_e64 s[4:5], 0, v42
	s_nop 1
	v_cndmask_b32_e64 v39, v39, v40, s[4:5]
	v_cmp_lt_f32_e64 s[4:5], 0, v43
	s_nop 1
	v_cndmask_b32_e64 v39, v39, v41, s[4:5]
	v_mul_f32_e32 v40, 0x37800000, v39
	v_cndmask_b32_e32 v39, v39, v40, vcc
	v_cmp_class_f32_e32 vcc, v38, v13
	s_nop 1
	v_cndmask_b32_e32 v38, v39, v38, vcc
	v_div_scale_f32 v39, s[4:5], v38, v38, 1.0
	v_rcp_f32_e32 v41, v39
	v_div_scale_f32 v40, vcc, 1.0, v38, 1.0
	v_fma_f32 v42, -v39, v41, 1.0
	v_fmac_f32_e32 v41, v42, v41
	v_mul_f32_e32 v42, v40, v41
	v_fma_f32 v43, -v39, v42, v40
	v_fmac_f32_e32 v42, v43, v41
	v_fma_f32 v39, -v39, v42, v40
	v_div_fmas_f32 v39, v39, v41, v42
	v_div_fixup_f32 v38, v39, v38, 1.0
	v_pk_mul_f32 v[22:23], v[22:23], v[38:39] op_sel_hi:[1,0]
	v_pk_mul_f32 v[24:25], v[24:25], v[38:39] op_sel_hi:[1,0]
	v_pk_fma_f32 v[14:15], v[14:15], v[22:23], v[18:19]
	v_pk_fma_f32 v[16:17], v[16:17], v[24:25], v[20:21]
	v_bfe_u32 v18, v14, 16, 1
	v_bfe_u32 v20, v16, 16, 1
	global_store_dwordx4 v[8:9], v[14:17], off sc1
	v_bfe_u32 v19, v15, 16, 1
	v_bfe_u32 v21, v17, 16, 1
	v_add3_u32 v14, v14, v18, s17
	v_add3_u32 v16, v16, v20, s17
	v_add3_u32 v15, v15, v19, s17
	v_add3_u32 v17, v17, v21, s17
	v_lshrrev_b32_e32 v14, 16, v14
	v_lshrrev_b32_e32 v16, 16, v16
	v_and_or_b32 v14, v15, s19, v14
	v_and_or_b32 v15, v17, s19, v16
	global_store_dwordx2 v[10:11], v[14:15], off sc1
	global_load_dwordx4 v[14:17], v[86:87], off offset:1024
	s_nop 0
	global_load_dwordx4 v[18:21], v[0:1], off offset:1024
	v_pk_mul_f32 v[22:23], v[28:29], v[38:39] op_sel_hi:[1,0]
	v_pk_mul_f32 v[24:25], v[26:27], v[38:39] op_sel_hi:[1,0]
	s_waitcnt vmcnt(0)
	v_pk_fma_f32 v[16:17], v[20:21], v[22:23], v[16:17]
	v_pk_fma_f32 v[14:15], v[18:19], v[24:25], v[14:15]
	v_bfe_u32 v20, v16, 16, 1
	v_bfe_u32 v18, v14, 16, 1
	global_store_dwordx4 v[8:9], v[14:17], off offset:1024 sc1
	v_bfe_u32 v19, v15, 16, 1
	v_bfe_u32 v21, v17, 16, 1
	v_add3_u32 v14, v14, v18, s17
	v_add3_u32 v16, v16, v20, s17
	v_add3_u32 v15, v15, v19, s17
	v_add3_u32 v17, v17, v21, s17
	v_lshrrev_b32_e32 v14, 16, v14
	v_lshrrev_b32_e32 v16, 16, v16
	v_and_or_b32 v14, v15, s19, v14
	v_and_or_b32 v15, v17, s19, v16
	global_store_dwordx2 v[10:11], v[14:15], off offset:512 sc1
	global_load_dwordx4 v[14:17], v[86:87], off offset:2048
	s_nop 0
	global_load_dwordx4 v[18:21], v[0:1], off offset:2048
	v_pk_mul_f32 v[22:23], v[32:33], v[38:39] op_sel_hi:[1,0]
	v_pk_mul_f32 v[24:25], v[30:31], v[38:39] op_sel_hi:[1,0]
	s_waitcnt vmcnt(0)
	v_pk_fma_f32 v[16:17], v[22:23], v[20:21], v[16:17]
	v_pk_fma_f32 v[14:15], v[24:25], v[18:19], v[14:15]
	v_bfe_u32 v20, v16, 16, 1
	v_bfe_u32 v18, v14, 16, 1
	global_store_dwordx4 v[8:9], v[14:17], off offset:2048 sc1
	v_bfe_u32 v19, v15, 16, 1
	v_bfe_u32 v21, v17, 16, 1
	v_add3_u32 v14, v14, v18, s17
	v_add3_u32 v16, v16, v20, s17
	v_add3_u32 v15, v15, v19, s17
	v_add3_u32 v17, v17, v21, s17
	v_lshrrev_b32_e32 v14, 16, v14
	v_lshrrev_b32_e32 v16, 16, v16
	v_and_or_b32 v14, v15, s19, v14
	v_and_or_b32 v15, v17, s19, v16
	global_store_dwordx2 v[10:11], v[14:15], off offset:1024 sc1
	global_load_dwordx4 v[14:17], v[86:87], off offset:3072
	s_nop 0
	global_load_dwordx4 v[18:21], v[0:1], off offset:3072
	v_pk_mul_f32 v[22:23], v[36:37], v[38:39] op_sel_hi:[1,0]
	v_pk_mul_f32 v[24:25], v[34:35], v[38:39] op_sel_hi:[1,0]
	s_waitcnt vmcnt(0)
	v_pk_fma_f32 v[16:17], v[22:23], v[20:21], v[16:17]
	v_pk_fma_f32 v[14:15], v[24:25], v[18:19], v[14:15]
	global_store_dwordx4 v[8:9], v[14:17], off offset:3072 sc1
	v_bfe_u32 v8, v14, 16, 1
	v_bfe_u32 v18, v16, 16, 1
	v_bfe_u32 v9, v15, 16, 1
	v_bfe_u32 v19, v17, 16, 1
	v_add3_u32 v8, v14, v8, s17
	v_add3_u32 v14, v16, v18, s17
	v_add3_u32 v9, v15, v9, s17
	v_add3_u32 v15, v17, v19, s17
	v_lshrrev_b32_e32 v8, 16, v8
	v_lshrrev_b32_e32 v14, 16, v14
	v_and_or_b32 v8, v9, s19, v8
	v_and_or_b32 v9, v15, s19, v14
	global_store_dwordx2 v[10:11], v[8:9], off offset:1536 sc1
	s_cbranch_scc0 .LBB0_1062
.LBB0_1063:
	s_waitcnt vmcnt(0)
	s_and_b64 vcc, exec, s[94:95]
	s_waitcnt lgkmcnt(0)
	s_barrier
	s_cbranch_vccnz .LBB0_1068
	v_mbcnt_lo_u32_b32 v0, -1, 0
	v_mbcnt_hi_u32_b32 v0, -1, v0
	s_nop 0
	v_cmp_eq_u32_e32 vcc, 0, v0
	s_and_saveexec_b64 s[4:5], vcc
	s_cbranch_execz .LBB0_1067
	s_mov_b64 s[16:17], exec
	v_mbcnt_lo_u32_b32 v0, s16, 0
	s_waitcnt vmcnt(0)
	s_waitcnt vmcnt(0)
	v_mbcnt_hi_u32_b32 v0, s17, v0
	v_cmp_eq_u32_e32 vcc, 0, v0
	s_and_b64 s[0:1], exec, vcc
	s_mov_b64 exec, s[0:1]
	s_cbranch_execz .LBB0_1067
	s_bcnt1_i32_b64 s0, s[16:17]
	v_mov_b32_e32 v0, 0
	v_mov_b32_e32 v1, s0
	global_atomic_add v0, v1, s[12:13]
